# final top-256 selection also retries with bins over the whole key range (then the second-level histogram) instead of falling back to the compiled exact code when fewer than 256 entries lie within six
# speedup vs baseline: 1.0012x; 1.0012x over previous
.LBB0_223:
	v_or_b32_e32 v9, s54, v143
	v_lshl_add_u32 v23, v9, 2, 0
	v_add_u32_e32 v15, 0x24000, v23
	ds_read_b32 v8, v15
	s_movk_i32 s2, 0x100
	s_waitcnt lgkmcnt(0)
	v_cmp_lt_i32_e32 vcc, s2, v8
	s_and_saveexec_b64 s[2:3], vcc
	s_cbranch_execz .LBB0_222
	v_readfirstlane_b32 s8, v9
	v_readfirstlane_b32 s24, v143
	s_mul_i32 s9, s8, 0xc00
	s_mul_i32 s10, s8, 0x600
	s_add_i32 s10, s10, 0x18000
	s_lshl_b32 s11, s8, 2
	s_add_i32 s11, s11, 0x24000
	v_mov_b32_e32 v40, s11
	ds_read_b32 v92, v40
	s_waitcnt lgkmcnt(0)
	v_readfirstlane_b32 s12, v92
	s_add_i32 s13, s12, -1
	v_min_u32_e32 v93, s13, v190
	v_lshl_add_u32 v94, v93, 2, s9
	v_lshl_add_u32 v93, v93, 1, s10
	ds_read_b32 v161, v94
	ds_read_u16 v142, v93
	v_min_u32_e32 v95, s13, v185
	v_lshl_add_u32 v120, v95, 2, s9
	v_lshl_add_u32 v95, v95, 1, s10
	ds_read_b32 v162, v120
	ds_read_u16 v143, v95
	v_min_u32_e32 v93, s13, v192
	v_lshl_add_u32 v94, v93, 2, s9
	v_lshl_add_u32 v93, v93, 1, s10
	ds_read_b32 v163, v94
	ds_read_u16 v144, v93
	v_min_u32_e32 v95, s13, v191
	v_lshl_add_u32 v120, v95, 2, s9
	v_lshl_add_u32 v95, v95, 1, s10
	ds_read_b32 v164, v120
	ds_read_u16 v145, v95
	v_min_u32_e32 v93, s13, v0
	v_lshl_add_u32 v94, v93, 2, s9
	v_lshl_add_u32 v93, v93, 1, s10
	ds_read_b32 v165, v94
	ds_read_u16 v146, v93
	v_min_u32_e32 v95, s13, v1
	v_lshl_add_u32 v120, v95, 2, s9
	v_lshl_add_u32 v95, v95, 1, s10
	ds_read_b32 v166, v120
	ds_read_u16 v148, v95
	v_min_u32_e32 v93, s13, v2
	v_lshl_add_u32 v94, v93, 2, s9
	v_lshl_add_u32 v93, v93, 1, s10
	ds_read_b32 v167, v94
	ds_read_u16 v149, v93
	v_min_u32_e32 v95, s13, v3
	v_lshl_add_u32 v120, v95, 2, s9
	v_lshl_add_u32 v95, v95, 1, s10
	ds_read_b32 v168, v120
	ds_read_u16 v150, v95
	v_min_u32_e32 v93, s13, v6
	v_lshl_add_u32 v94, v93, 2, s9
	v_lshl_add_u32 v93, v93, 1, s10
	ds_read_b32 v169, v94
	ds_read_u16 v152, v93
	v_min_u32_e32 v95, s13, v7
	v_lshl_add_u32 v120, v95, 2, s9
	v_lshl_add_u32 v95, v95, 1, s10
	ds_read_b32 v170, v120
	ds_read_u16 v153, v95
	v_min_u32_e32 v93, s13, v4
	v_lshl_add_u32 v94, v93, 2, s9
	v_lshl_add_u32 v93, v93, 1, s10
	ds_read_b32 v171, v94
	ds_read_u16 v159, v93
	v_min_u32_e32 v95, s13, v5
	v_lshl_add_u32 v120, v95, 2, s9
	v_lshl_add_u32 v95, v95, 1, s10
	ds_read_b32 v172, v120
	ds_read_u16 v160, v95
	ds_write_b128 v127, a[206:209]
	s_waitcnt lgkmcnt(1)
	v_ashrrev_i32_e32 v93, 31, v161
	v_or_b32_e32 v93, 0x80000000, v93
	v_xor_b32_e32 v108, v161, v93
	v_ashrrev_i32_e32 v94, 31, v162
	v_or_b32_e32 v94, 0x80000000, v94
	v_xor_b32_e32 v109, v162, v94
	v_ashrrev_i32_e32 v93, 31, v163
	v_or_b32_e32 v93, 0x80000000, v93
	v_xor_b32_e32 v110, v163, v93
	v_ashrrev_i32_e32 v94, 31, v164
	v_or_b32_e32 v94, 0x80000000, v94
	v_xor_b32_e32 v111, v164, v94
	v_ashrrev_i32_e32 v93, 31, v165
	v_or_b32_e32 v93, 0x80000000, v93
	v_xor_b32_e32 v112, v165, v93
	v_ashrrev_i32_e32 v94, 31, v166
	v_or_b32_e32 v94, 0x80000000, v94
	v_xor_b32_e32 v113, v166, v94
	v_ashrrev_i32_e32 v93, 31, v167
	v_or_b32_e32 v93, 0x80000000, v93
	v_xor_b32_e32 v114, v167, v93
	v_ashrrev_i32_e32 v94, 31, v168
	v_or_b32_e32 v94, 0x80000000, v94
	v_xor_b32_e32 v115, v168, v94
	v_ashrrev_i32_e32 v93, 31, v169
	v_or_b32_e32 v93, 0x80000000, v93
	v_xor_b32_e32 v116, v169, v93
	v_ashrrev_i32_e32 v94, 31, v170
	v_or_b32_e32 v94, 0x80000000, v94
	v_xor_b32_e32 v117, v170, v94
	v_ashrrev_i32_e32 v93, 31, v171
	v_or_b32_e32 v93, 0x80000000, v93
	v_xor_b32_e32 v118, v171, v93
	v_ashrrev_i32_e32 v94, 31, v172
	v_or_b32_e32 v94, 0x80000000, v94
	v_xor_b32_e32 v119, v172, v94
	v_max3_u32 v92, v108, v109, v110
	v_min3_u32 v93, v108, v109, v110
	v_max3_u32 v92, v111, v112, v92
	v_min3_u32 v93, v111, v112, v93
	v_max3_u32 v92, v113, v114, v92
	v_min3_u32 v93, v113, v114, v93
	v_max3_u32 v92, v115, v116, v92
	v_min3_u32 v93, v115, v116, v93
	v_max3_u32 v92, v117, v118, v92
	v_min3_u32 v93, v117, v118, v93
	v_max_u32_e32 v92, v119, v92
	v_min_u32_e32 v93, v119, v93
	s_nop 0
	v_max_u32_dpp v92, v92, v92 quad_perm:[1,0,3,2] row_mask:0xf bank_mask:0xf bound_ctrl:1
	v_min_u32_dpp v93, v93, v93 quad_perm:[1,0,3,2] row_mask:0xf bank_mask:0xf bound_ctrl:1
	s_nop 0
	v_max_u32_dpp v92, v92, v92 quad_perm:[2,3,0,1] row_mask:0xf bank_mask:0xf bound_ctrl:1
	v_min_u32_dpp v93, v93, v93 quad_perm:[2,3,0,1] row_mask:0xf bank_mask:0xf bound_ctrl:1
	s_nop 0
	v_max_u32_dpp v92, v92, v92 row_half_mirror row_mask:0xf bank_mask:0xf bound_ctrl:1
	v_min_u32_dpp v93, v93, v93 row_half_mirror row_mask:0xf bank_mask:0xf bound_ctrl:1
	s_nop 0
	v_max_u32_dpp v92, v92, v92 row_mirror row_mask:0xf bank_mask:0xf bound_ctrl:1
	v_min_u32_dpp v93, v93, v93 row_mirror row_mask:0xf bank_mask:0xf bound_ctrl:1
	s_nop 1
	v_readlane_b32 s15, v92, 0
	v_readlane_b32 s16, v92, 16
	v_readlane_b32 s17, v92, 32
	v_readlane_b32 s18, v92, 48
	s_max_u32 s15, s15, s16
	s_max_u32 s17, s17, s18
	s_max_u32 s15, s15, s17
	v_readlane_b32 s16, v93, 0
	v_readlane_b32 s17, v93, 16
	v_readlane_b32 s18, v93, 32
	v_readlane_b32 s19, v93, 48
	s_min_u32 s16, s16, s17
	s_min_u32 s18, s18, s19
	s_min_u32 s16, s16, s18
	s_sub_u32 s17, s15, 0x3000000
	s_cselect_b32 s17, 0, s17
	s_mov_b32 s25, s16
	s_max_u32 s14, s16, s17
.Lfn_rebin:
	s_sub_u32 s16, s15, s14
	s_add_u32 s16, s16, 1
	s_cmpk_le_u32 s16, 0x100
	s_cbranch_scc1 .Lfn_orig
	v_mov_b32_e32 v92, s16
	v_cvt_f32_u32_e32 v92, v92
	v_rcp_f32_e32 v92, v92
	s_nop 0
	v_mul_f32_e32 v92, 0x53800000, v92
	v_cvt_u32_f32_e32 v92, v92
	s_nop 0
	v_readfirstlane_b32 s21, v92
	s_nop 1
	v_max_u32_e32 v93, s14, v108
	v_subrev_u32_e32 v93, s14, v93
	v_mul_hi_u32 v93, v93, s21
	v_min_u32_e32 v173, 0xff, v93
	v_max_u32_e32 v94, s14, v109
	v_subrev_u32_e32 v94, s14, v94
	v_mul_hi_u32 v94, v94, s21
	v_min_u32_e32 v174, 0xff, v94
	v_max_u32_e32 v95, s14, v110
	v_subrev_u32_e32 v95, s14, v95
	v_mul_hi_u32 v95, v95, s21
	v_min_u32_e32 v175, 0xff, v95
	v_max_u32_e32 v93, s14, v111
	v_subrev_u32_e32 v93, s14, v93
	v_mul_hi_u32 v93, v93, s21
	v_min_u32_e32 v176, 0xff, v93
	v_max_u32_e32 v94, s14, v112
	v_subrev_u32_e32 v94, s14, v94
	v_mul_hi_u32 v94, v94, s21
	v_min_u32_e32 v177, 0xff, v94
	v_max_u32_e32 v95, s14, v113
	v_subrev_u32_e32 v95, s14, v95
	v_mul_hi_u32 v95, v95, s21
	v_min_u32_e32 v178, 0xff, v95
	v_max_u32_e32 v93, s14, v114
	v_subrev_u32_e32 v93, s14, v93
	v_mul_hi_u32 v93, v93, s21
	v_min_u32_e32 v179, 0xff, v93
	v_max_u32_e32 v94, s14, v115
	v_subrev_u32_e32 v94, s14, v94
	v_mul_hi_u32 v94, v94, s21
	v_min_u32_e32 v180, 0xff, v94
	v_max_u32_e32 v95, s14, v116
	v_subrev_u32_e32 v95, s14, v95
	v_mul_hi_u32 v95, v95, s21
	v_min_u32_e32 v181, 0xff, v95
	v_max_u32_e32 v93, s14, v117
	v_subrev_u32_e32 v93, s14, v93
	v_mul_hi_u32 v93, v93, s21
	v_min_u32_e32 v182, 0xff, v93
	v_max_u32_e32 v94, s14, v118
	v_subrev_u32_e32 v94, s14, v94
	v_mul_hi_u32 v94, v94, s21
	v_min_u32_e32 v183, 0xff, v94
	v_max_u32_e32 v95, s14, v119
	v_subrev_u32_e32 v95, s14, v95
	v_mul_hi_u32 v95, v95, s21
	v_min_u32_e32 v184, 0xff, v95
	v_cmp_gt_u32_e64 s[26:27], s12, v190
	v_cmp_gt_u32_e64 s[28:29], s12, v185
	v_cmp_gt_u32_e64 s[30:31], s12, v192
	v_cndmask_b32_e64 v173, 0, v173, s[26:27]
	v_cmp_gt_u32_e64 s[26:27], s12, v191
	v_cndmask_b32_e64 v174, 0, v174, s[28:29]
	v_cmp_gt_u32_e64 s[28:29], s12, v0
	v_cndmask_b32_e64 v175, 0, v175, s[30:31]
	v_cmp_gt_u32_e64 s[30:31], s12, v1
	v_cndmask_b32_e64 v176, 0, v176, s[26:27]
	v_cmp_gt_u32_e64 s[26:27], s12, v2
	v_cndmask_b32_e64 v177, 0, v177, s[28:29]
	v_cmp_gt_u32_e64 s[28:29], s12, v3
	v_cndmask_b32_e64 v178, 0, v178, s[30:31]
	v_cmp_gt_u32_e64 s[30:31], s12, v6
	v_cndmask_b32_e64 v179, 0, v179, s[26:27]
	v_cmp_gt_u32_e64 s[26:27], s12, v7
	v_cndmask_b32_e64 v180, 0, v180, s[28:29]
	v_cmp_gt_u32_e64 s[28:29], s12, v4
	v_cndmask_b32_e64 v181, 0, v181, s[30:31]
	v_cmp_gt_u32_e64 s[30:31], s12, v5
	v_cndmask_b32_e64 v182, 0, v182, s[26:27]
	s_nop 0
	v_cndmask_b32_e64 v183, 0, v183, s[28:29]
	v_cndmask_b32_e64 v184, 0, v184, s[30:31]
	s_mov_b64 s[22:23], exec
	v_cmp_ne_u32_e64 s[26:27], 0, v173
	v_lshl_add_u32 v93, v173, 2, v121
	s_mov_b64 exec, s[26:27]
	ds_add_u32 v93, v252
	s_mov_b64 exec, s[22:23]
	v_cmp_ne_u32_e64 s[28:29], 0, v174
	v_lshl_add_u32 v94, v174, 2, v121
	s_mov_b64 exec, s[28:29]
	ds_add_u32 v94, v252
	s_mov_b64 exec, s[22:23]
	v_cmp_ne_u32_e64 s[30:31], 0, v175
	v_lshl_add_u32 v95, v175, 2, v121
	s_mov_b64 exec, s[30:31]
	ds_add_u32 v95, v252
	s_mov_b64 exec, s[22:23]
	v_cmp_ne_u32_e64 s[26:27], 0, v176
	v_lshl_add_u32 v93, v176, 2, v121
	s_mov_b64 exec, s[26:27]
	ds_add_u32 v93, v252
	s_mov_b64 exec, s[22:23]
	v_cmp_ne_u32_e64 s[28:29], 0, v177
	v_lshl_add_u32 v94, v177, 2, v121
	s_mov_b64 exec, s[28:29]
	ds_add_u32 v94, v252
	s_mov_b64 exec, s[22:23]
	v_cmp_ne_u32_e64 s[30:31], 0, v178
	v_lshl_add_u32 v95, v178, 2, v121
	s_mov_b64 exec, s[30:31]
	ds_add_u32 v95, v252
	s_mov_b64 exec, s[22:23]
	v_cmp_ne_u32_e64 s[26:27], 0, v179
	v_lshl_add_u32 v93, v179, 2, v121
	s_mov_b64 exec, s[26:27]
	ds_add_u32 v93, v252
	s_mov_b64 exec, s[22:23]
	v_cmp_ne_u32_e64 s[28:29], 0, v180
	v_lshl_add_u32 v94, v180, 2, v121
	s_mov_b64 exec, s[28:29]
	ds_add_u32 v94, v252
	s_mov_b64 exec, s[22:23]
	v_cmp_ne_u32_e64 s[30:31], 0, v181
	v_lshl_add_u32 v95, v181, 2, v121
	s_mov_b64 exec, s[30:31]
	ds_add_u32 v95, v252
	s_mov_b64 exec, s[22:23]
	v_cmp_ne_u32_e64 s[26:27], 0, v182
	v_lshl_add_u32 v93, v182, 2, v121
	s_mov_b64 exec, s[26:27]
	ds_add_u32 v93, v252
	s_mov_b64 exec, s[22:23]
	v_cmp_ne_u32_e64 s[28:29], 0, v183
	v_lshl_add_u32 v94, v183, 2, v121
	s_mov_b64 exec, s[28:29]
	ds_add_u32 v94, v252
	s_mov_b64 exec, s[22:23]
	v_cmp_ne_u32_e64 s[30:31], 0, v184
	v_lshl_add_u32 v95, v184, 2, v121
	s_mov_b64 exec, s[30:31]
	ds_add_u32 v95, v252
	s_mov_b64 exec, s[22:23]
	ds_read_b128 v[92:95], v127
	s_waitcnt lgkmcnt(0)
	v_add_u32_e32 v120, v92, v93
	v_add3_u32 v120, v120, v94, v95
	v_mov_b32_e32 v122, v120
	s_nop 1
	v_add_u32_dpp v122, v122, v122 row_shr:1 row_mask:0xf bank_mask:0xf bound_ctrl:1
	s_nop 1
	v_add_u32_dpp v122, v122, v122 row_shr:2 row_mask:0xf bank_mask:0xf bound_ctrl:1
	s_nop 1
	v_add_u32_dpp v122, v122, v122 row_shr:4 row_mask:0xf bank_mask:0xf bound_ctrl:1
	s_nop 1
	v_add_u32_dpp v122, v122, v122 row_shr:8 row_mask:0xf bank_mask:0xf bound_ctrl:1
	s_nop 1
	v_add_u32_dpp v122, v122, v122 row_bcast:15 row_mask:0xa bank_mask:0xf
	s_nop 1
	v_add_u32_dpp v122, v122, v122 row_bcast:31 row_mask:0xc bank_mask:0xf
	s_nop 1
	v_readlane_b32 s16, v122, 63
	s_nop 1
	v_sub_u32_e32 v123, s16, v122
	v_add_u32_e32 v124, v123, v95
	v_add_u32_e32 v126, v124, v94
	v_add_u32_e32 v128, v126, v93
	v_add_u32_e32 v129, v128, v92
	s_movk_i32 s17, 0x100
	v_lshlrev_b32_e32 v130, 2, v190
	v_cmp_le_u32_e64 s[26:27], s17, v128
	v_cmp_le_u32_e64 s[28:29], s17, v126
	v_cmp_le_u32_e64 s[30:31], s17, v124
	v_mov_b32_e32 v134, v130
	v_or_b32_e32 v131, 1, v134
	v_cndmask_b32_e64 v129, v129, v128, s[26:27]
	v_cndmask_b32_e64 v130, v130, v131, s[26:27]
	v_or_b32_e32 v131, 2, v134
	v_cndmask_b32_e64 v129, v129, v126, s[28:29]
	v_cndmask_b32_e64 v130, v130, v131, s[28:29]
	v_or_b32_e32 v131, 3, v134
	v_cndmask_b32_e64 v129, v129, v124, s[30:31]
	v_cndmask_b32_e64 v130, v130, v131, s[30:31]
	v_add_u32_e32 v132, v123, v120
	v_cmp_gt_u32_e64 s[26:27], s17, v123
	v_cmp_le_u32_e64 s[28:29], s17, v132
	s_nop 0
	s_and_b64 s[26:27], s[26:27], s[28:29]
	s_cmp_eq_u64 s[26:27], 0
	s_cbranch_scc1 .Lfn_retry
	s_ff1_i32_b64 s18, s[26:27]
	s_nop 3
	v_readlane_b32 s19, v129, s18
	v_readlane_b32 s20, v130, s18
	s_cmp_eq_u32 s20, 0
	s_cbranch_scc1 .Lfn_retry
	v_mov_b32_e32 v92, s21
	v_cvt_f32_u32_e32 v92, v92
	v_rcp_f32_e32 v92, v92
	v_mov_b32_e32 v93, s20
	v_cvt_f32_u32_e32 v93, v93
	v_mul_f32_e32 v92, 0x4f800000, v92
	v_mul_f32_e32 v92, v92, v93
	v_mul_f32_e32 v92, 0x3f7ffff0, v92
	v_cvt_u32_f32_e32 v92, v92
	s_nop 0
	v_readfirstlane_b32 s16, v92
	s_add_u32 s16, s16, s14
	s_mov_b32 s13, s16
	v_mov_b32_e32 v136, 0
	v_cmp_eq_u32_e64 s[26:27], s20, v173
	v_cmp_eq_u32_e64 s[28:29], s20, v174
	v_cmp_eq_u32_e64 s[30:31], s20, v175
	v_addc_co_u32_e64 v136, vcc, 0, v136, s[26:27]
	v_cmp_eq_u32_e64 s[26:27], s20, v176
	v_addc_co_u32_e64 v136, vcc, 0, v136, s[28:29]
	v_cmp_eq_u32_e64 s[28:29], s20, v177
	v_addc_co_u32_e64 v136, vcc, 0, v136, s[30:31]
	v_cmp_eq_u32_e64 s[30:31], s20, v178
	v_addc_co_u32_e64 v136, vcc, 0, v136, s[26:27]
	v_cmp_eq_u32_e64 s[26:27], s20, v179
	v_addc_co_u32_e64 v136, vcc, 0, v136, s[28:29]
	v_cmp_eq_u32_e64 s[28:29], s20, v180
	v_addc_co_u32_e64 v136, vcc, 0, v136, s[30:31]
	v_cmp_eq_u32_e64 s[30:31], s20, v181
	v_addc_co_u32_e64 v136, vcc, 0, v136, s[26:27]
	v_cmp_eq_u32_e64 s[26:27], s20, v182
	v_addc_co_u32_e64 v136, vcc, 0, v136, s[28:29]
	v_cmp_eq_u32_e64 s[28:29], s20, v183
	v_addc_co_u32_e64 v136, vcc, 0, v136, s[30:31]
	v_cmp_eq_u32_e64 s[30:31], s20, v184
	v_addc_co_u32_e64 v136, vcc, 0, v136, s[26:27]
	s_nop 0
	v_addc_co_u32_e64 v136, vcc, 0, v136, s[28:29]
	v_addc_co_u32_e64 v136, vcc, 0, v136, s[30:31]
	s_nop 1
	v_add_u32_dpp v136, v136, v136 quad_perm:[1,0,3,2] row_mask:0xf bank_mask:0xf bound_ctrl:1
	s_nop 1
	v_add_u32_dpp v136, v136, v136 quad_perm:[2,3,0,1] row_mask:0xf bank_mask:0xf bound_ctrl:1
	s_nop 1
	v_add_u32_dpp v136, v136, v136 row_half_mirror row_mask:0xf bank_mask:0xf bound_ctrl:1
	s_nop 1
	v_add_u32_dpp v136, v136, v136 row_mirror row_mask:0xf bank_mask:0xf bound_ctrl:1
	s_nop 1
	v_readlane_b32 s14, v136, 0
	v_readlane_b32 s15, v136, 16
	v_readlane_b32 s17, v136, 32
	v_readlane_b32 s18, v136, 48
	s_add_i32 s14, s14, s15
	s_add_i32 s17, s17, s18
	s_add_i32 s14, s14, s17
	s_sub_i32 s15, s19, s14
	s_sub_i32 s15, 0x100, s15
	s_sub_i32 s25, s14, s15
	s_cmp_eq_u32 s25, 0
	s_cbranch_scc1 .Lfn_nodrop
	s_cmpk_le_u32 s25, 3
	s_cbranch_scc1 .Lfn_direct
	v_mov_b32_e32 v92, s21
	v_cvt_f32_u32_e32 v92, v92
	v_rcp_f32_e32 v92, v92
	s_nop 0
	v_mul_f32_e32 v92, 0x4f800000, v92
	v_mul_f32_e32 v92, 0x3f800008, v92
	v_cvt_u32_f32_e32 v92, v92
	v_add_u32_e32 v92, 0x40, v92
	v_cvt_f32_u32_e32 v93, v92
	v_rcp_f32_e32 v93, v93
	s_nop 0
	v_mul_f32_e32 v93, 0x53800000, v93
	v_cvt_u32_f32_e32 v93, v93
	s_nop 0
	v_readfirstlane_b32 s17, v92
	v_readfirstlane_b32 s18, v93
	s_cmpk_le_u32 s17, 0x100
	s_cbranch_scc1 .Lfn_orig
	ds_write_b128 v127, a[206:209]
	s_mov_b64 s[22:23], exec
	v_cmp_eq_u32_e64 s[26:27], s20, v173
	v_subrev_u32_e32 v93, s13, v108
	v_mul_hi_u32 v93, v93, s18
	v_min_u32_e32 v120, 0xff, v93
	v_lshl_add_u32 v93, v120, 2, v121
	s_mov_b64 exec, s[26:27]
	ds_add_u32 v93, v252
	s_mov_b64 exec, s[22:23]
	v_cmp_eq_u32_e64 s[28:29], s20, v174
	v_subrev_u32_e32 v94, s13, v109
	v_mul_hi_u32 v94, v94, s18
	v_min_u32_e32 v122, 0xff, v94
	v_lshl_add_u32 v94, v122, 2, v121
	s_mov_b64 exec, s[28:29]
	ds_add_u32 v94, v252
	s_mov_b64 exec, s[22:23]
	v_cmp_eq_u32_e64 s[30:31], s20, v175
	v_subrev_u32_e32 v95, s13, v110
	v_mul_hi_u32 v95, v95, s18
	v_min_u32_e32 v123, 0xff, v95
	v_lshl_add_u32 v95, v123, 2, v121
	s_mov_b64 exec, s[30:31]
	ds_add_u32 v95, v252
	s_mov_b64 exec, s[22:23]
	v_cmp_eq_u32_e64 s[26:27], s20, v176
	v_subrev_u32_e32 v93, s13, v111
	v_mul_hi_u32 v93, v93, s18
	v_min_u32_e32 v124, 0xff, v93
	v_lshl_add_u32 v93, v124, 2, v121
	s_mov_b64 exec, s[26:27]
	ds_add_u32 v93, v252
	s_mov_b64 exec, s[22:23]
	v_cmp_eq_u32_e64 s[28:29], s20, v177
	v_subrev_u32_e32 v94, s13, v112
	v_mul_hi_u32 v94, v94, s18
	v_min_u32_e32 v126, 0xff, v94
	v_lshl_add_u32 v94, v126, 2, v121
	s_mov_b64 exec, s[28:29]
	ds_add_u32 v94, v252
	s_mov_b64 exec, s[22:23]
	v_cmp_eq_u32_e64 s[30:31], s20, v178
	v_subrev_u32_e32 v95, s13, v113
	v_mul_hi_u32 v95, v95, s18
	v_min_u32_e32 v128, 0xff, v95
	v_lshl_add_u32 v95, v128, 2, v121
	s_mov_b64 exec, s[30:31]
	ds_add_u32 v95, v252
	s_mov_b64 exec, s[22:23]
	v_cmp_eq_u32_e64 s[26:27], s20, v179
	v_subrev_u32_e32 v93, s13, v114
	v_mul_hi_u32 v93, v93, s18
	v_min_u32_e32 v129, 0xff, v93
	v_lshl_add_u32 v93, v129, 2, v121
	s_mov_b64 exec, s[26:27]
	ds_add_u32 v93, v252
	s_mov_b64 exec, s[22:23]
	v_cmp_eq_u32_e64 s[28:29], s20, v180
	v_subrev_u32_e32 v94, s13, v115
	v_mul_hi_u32 v94, v94, s18
	v_min_u32_e32 v130, 0xff, v94
	v_lshl_add_u32 v94, v130, 2, v121
	s_mov_b64 exec, s[28:29]
	ds_add_u32 v94, v252
	s_mov_b64 exec, s[22:23]
	v_cmp_eq_u32_e64 s[30:31], s20, v181
	v_subrev_u32_e32 v95, s13, v116
	v_mul_hi_u32 v95, v95, s18
	v_min_u32_e32 v131, 0xff, v95
	v_lshl_add_u32 v95, v131, 2, v121
	s_mov_b64 exec, s[30:31]
	ds_add_u32 v95, v252
	s_mov_b64 exec, s[22:23]
	v_cmp_eq_u32_e64 s[26:27], s20, v182
	v_subrev_u32_e32 v93, s13, v117
	v_mul_hi_u32 v93, v93, s18
	v_min_u32_e32 v132, 0xff, v93
	v_lshl_add_u32 v93, v132, 2, v121
	s_mov_b64 exec, s[26:27]
	ds_add_u32 v93, v252
	s_mov_b64 exec, s[22:23]
	v_cmp_eq_u32_e64 s[28:29], s20, v183
	v_subrev_u32_e32 v94, s13, v118
	v_mul_hi_u32 v94, v94, s18
	v_min_u32_e32 v134, 0xff, v94
	v_lshl_add_u32 v94, v134, 2, v121
	s_mov_b64 exec, s[28:29]
	ds_add_u32 v94, v252
	s_mov_b64 exec, s[22:23]
	v_cmp_eq_u32_e64 s[30:31], s20, v184
	v_subrev_u32_e32 v95, s13, v119
	v_mul_hi_u32 v95, v95, s18
	v_min_u32_e32 v135, 0xff, v95
	v_lshl_add_u32 v95, v135, 2, v121
	s_mov_b64 exec, s[30:31]
	ds_add_u32 v95, v252
	s_mov_b64 exec, s[22:23]
	ds_read_b128 v[92:95], v127
	s_waitcnt lgkmcnt(0)
	v_add_u32_e32 v136, v92, v93
	v_add3_u32 v136, v136, v94, v95
	v_mov_b32_e32 v137, v136
	s_nop 1
	v_add_u32_dpp v137, v137, v137 row_shr:1 row_mask:0xf bank_mask:0xf bound_ctrl:1
	s_nop 1
	v_add_u32_dpp v137, v137, v137 row_shr:2 row_mask:0xf bank_mask:0xf bound_ctrl:1
	s_nop 1
	v_add_u32_dpp v137, v137, v137 row_shr:4 row_mask:0xf bank_mask:0xf bound_ctrl:1
	s_nop 1
	v_add_u32_dpp v137, v137, v137 row_shr:8 row_mask:0xf bank_mask:0xf bound_ctrl:1
	s_nop 1
	v_add_u32_dpp v137, v137, v137 row_bcast:15 row_mask:0xa bank_mask:0xf
	s_nop 1
	v_add_u32_dpp v137, v137, v137 row_bcast:31 row_mask:0xc bank_mask:0xf
	s_nop 1
	v_readlane_b32 s17, v137, 63
	s_nop 1
	v_sub_u32_e32 v138, s17, v137
	v_add_u32_e32 v140, v138, v95
	v_add_u32_e32 v95, v140, v94
	v_add_u32_e32 v94, v95, v93
	v_add_u32_e32 v93, v94, v92
	v_lshlrev_b32_e32 v92, 2, v190
	v_cmp_le_u32_e64 s[26:27], s15, v94
	v_cmp_le_u32_e64 s[28:29], s15, v95
	v_cmp_le_u32_e64 s[30:31], s15, v140
	v_mov_b32_e32 v137, v92
	v_mov_b32_e32 v136, v93
	v_or_b32_e32 v93, 1, v137
	v_cndmask_b32_e64 v136, v136, v94, s[26:27]
	v_cndmask_b32_e64 v92, v92, v93, s[26:27]
	v_or_b32_e32 v93, 2, v137
	v_cndmask_b32_e64 v136, v136, v95, s[28:29]
	v_cndmask_b32_e64 v92, v92, v93, s[28:29]
	v_or_b32_e32 v93, 3, v137
	v_cndmask_b32_e64 v136, v136, v140, s[30:31]
	v_cndmask_b32_e64 v92, v92, v93, s[30:31]
	v_add_u32_e32 v94, v138, v95
	v_cmp_gt_u32_e64 s[26:27], s15, v138
	v_cmp_le_u32_e64 s[28:29], s15, v136
	s_nop 0
	s_and_b64 s[26:27], s[26:27], s[28:29]
	s_cmp_eq_u64 s[26:27], 0
	s_cbranch_scc1 .Lfn_orig
	s_ff1_i32_b64 s17, s[26:27]
	s_nop 3
	v_readlane_b32 s25, v136, s17
	v_readlane_b32 s14, v92, s17
	s_sub_i32 s25, s25, s15
	s_cmpk_gt_u32 s25, 4
	s_cbranch_scc1 .Lfn_orig
	v_cmp_eq_u32_e64 s[26:27], s20, v173
	v_cmp_gt_u32_e64 s[28:29], s14, v120
	v_cmp_eq_u32_e64 s[30:31], s14, v120
	v_subrev_u32_e32 v93, s13, v108
	v_sub_u32_e32 v94, 0x3fff, v142
	s_and_b64 s[28:29], s[28:29], s[26:27]
	s_and_b64 s[30:31], s[30:31], s[26:27]
	v_lshl_or_b32 v93, v93, 14, v94
	s_nop 1
	v_cndmask_b32_e64 v173, v173, 0, s[28:29]
	v_cndmask_b32_e64 v120, -1, v93, s[30:31]
	v_cmp_eq_u32_e64 s[26:27], s20, v174
	v_cmp_gt_u32_e64 s[28:29], s14, v122
	v_cmp_eq_u32_e64 s[30:31], s14, v122
	v_subrev_u32_e32 v93, s13, v109
	v_sub_u32_e32 v94, 0x3fff, v143
	s_and_b64 s[28:29], s[28:29], s[26:27]
	s_and_b64 s[30:31], s[30:31], s[26:27]
	v_lshl_or_b32 v93, v93, 14, v94
	s_nop 1
	v_cndmask_b32_e64 v174, v174, 0, s[28:29]
	v_cndmask_b32_e64 v122, -1, v93, s[30:31]
	v_cmp_eq_u32_e64 s[26:27], s20, v175
	v_cmp_gt_u32_e64 s[28:29], s14, v123
	v_cmp_eq_u32_e64 s[30:31], s14, v123
	v_subrev_u32_e32 v93, s13, v110
	v_sub_u32_e32 v94, 0x3fff, v144
	s_and_b64 s[28:29], s[28:29], s[26:27]
	s_and_b64 s[30:31], s[30:31], s[26:27]
	v_lshl_or_b32 v93, v93, 14, v94
	s_nop 1
	v_cndmask_b32_e64 v175, v175, 0, s[28:29]
	v_cndmask_b32_e64 v123, -1, v93, s[30:31]
	v_cmp_eq_u32_e64 s[26:27], s20, v176
	v_cmp_gt_u32_e64 s[28:29], s14, v124
	v_cmp_eq_u32_e64 s[30:31], s14, v124
	v_subrev_u32_e32 v93, s13, v111
	v_sub_u32_e32 v94, 0x3fff, v145
	s_and_b64 s[28:29], s[28:29], s[26:27]
	s_and_b64 s[30:31], s[30:31], s[26:27]
	v_lshl_or_b32 v93, v93, 14, v94
	s_nop 1
	v_cndmask_b32_e64 v176, v176, 0, s[28:29]
	v_cndmask_b32_e64 v124, -1, v93, s[30:31]
	v_cmp_eq_u32_e64 s[26:27], s20, v177
	v_cmp_gt_u32_e64 s[28:29], s14, v126
	v_cmp_eq_u32_e64 s[30:31], s14, v126
	v_subrev_u32_e32 v93, s13, v112
	v_sub_u32_e32 v94, 0x3fff, v146
	s_and_b64 s[28:29], s[28:29], s[26:27]
	s_and_b64 s[30:31], s[30:31], s[26:27]
	v_lshl_or_b32 v93, v93, 14, v94
	s_nop 1
	v_cndmask_b32_e64 v177, v177, 0, s[28:29]
	v_cndmask_b32_e64 v126, -1, v93, s[30:31]
	v_cmp_eq_u32_e64 s[26:27], s20, v178
	v_cmp_gt_u32_e64 s[28:29], s14, v128
	v_cmp_eq_u32_e64 s[30:31], s14, v128
	v_subrev_u32_e32 v93, s13, v113
	v_sub_u32_e32 v94, 0x3fff, v148
	s_and_b64 s[28:29], s[28:29], s[26:27]
	s_and_b64 s[30:31], s[30:31], s[26:27]
	v_lshl_or_b32 v93, v93, 14, v94
	s_nop 1
	v_cndmask_b32_e64 v178, v178, 0, s[28:29]
	v_cndmask_b32_e64 v128, -1, v93, s[30:31]
	v_cmp_eq_u32_e64 s[26:27], s20, v179
	v_cmp_gt_u32_e64 s[28:29], s14, v129
	v_cmp_eq_u32_e64 s[30:31], s14, v129
	v_subrev_u32_e32 v93, s13, v114
	v_sub_u32_e32 v94, 0x3fff, v149
	s_and_b64 s[28:29], s[28:29], s[26:27]
	s_and_b64 s[30:31], s[30:31], s[26:27]
	v_lshl_or_b32 v93, v93, 14, v94
	s_nop 1
	v_cndmask_b32_e64 v179, v179, 0, s[28:29]
	v_cndmask_b32_e64 v129, -1, v93, s[30:31]
	v_cmp_eq_u32_e64 s[26:27], s20, v180
	v_cmp_gt_u32_e64 s[28:29], s14, v130
	v_cmp_eq_u32_e64 s[30:31], s14, v130
	v_subrev_u32_e32 v93, s13, v115
	v_sub_u32_e32 v94, 0x3fff, v150
	s_and_b64 s[28:29], s[28:29], s[26:27]
	s_and_b64 s[30:31], s[30:31], s[26:27]
	v_lshl_or_b32 v93, v93, 14, v94
	s_nop 1
	v_cndmask_b32_e64 v180, v180, 0, s[28:29]
	v_cndmask_b32_e64 v130, -1, v93, s[30:31]
	v_cmp_eq_u32_e64 s[26:27], s20, v181
	v_cmp_gt_u32_e64 s[28:29], s14, v131
	v_cmp_eq_u32_e64 s[30:31], s14, v131
	v_subrev_u32_e32 v93, s13, v116
	v_sub_u32_e32 v94, 0x3fff, v152
	s_and_b64 s[28:29], s[28:29], s[26:27]
	s_and_b64 s[30:31], s[30:31], s[26:27]
	v_lshl_or_b32 v93, v93, 14, v94
	s_nop 1
	v_cndmask_b32_e64 v181, v181, 0, s[28:29]
	v_cndmask_b32_e64 v131, -1, v93, s[30:31]
	v_cmp_eq_u32_e64 s[26:27], s20, v182
	v_cmp_gt_u32_e64 s[28:29], s14, v132
	v_cmp_eq_u32_e64 s[30:31], s14, v132
	v_subrev_u32_e32 v93, s13, v117
	v_sub_u32_e32 v94, 0x3fff, v153
	s_and_b64 s[28:29], s[28:29], s[26:27]
	s_and_b64 s[30:31], s[30:31], s[26:27]
	v_lshl_or_b32 v93, v93, 14, v94
	s_nop 1
	v_cndmask_b32_e64 v182, v182, 0, s[28:29]
	v_cndmask_b32_e64 v132, -1, v93, s[30:31]
	v_cmp_eq_u32_e64 s[26:27], s20, v183
	v_cmp_gt_u32_e64 s[28:29], s14, v134
	v_cmp_eq_u32_e64 s[30:31], s14, v134
	v_subrev_u32_e32 v93, s13, v118
	v_sub_u32_e32 v94, 0x3fff, v159
	s_and_b64 s[28:29], s[28:29], s[26:27]
	s_and_b64 s[30:31], s[30:31], s[26:27]
	v_lshl_or_b32 v93, v93, 14, v94
	s_nop 1
	v_cndmask_b32_e64 v183, v183, 0, s[28:29]
	v_cndmask_b32_e64 v134, -1, v93, s[30:31]
	v_cmp_eq_u32_e64 s[26:27], s20, v184
	v_cmp_gt_u32_e64 s[28:29], s14, v135
	v_cmp_eq_u32_e64 s[30:31], s14, v135
	v_subrev_u32_e32 v93, s13, v119
	v_sub_u32_e32 v94, 0x3fff, v160
	s_and_b64 s[28:29], s[28:29], s[26:27]
	s_and_b64 s[30:31], s[30:31], s[26:27]
	v_lshl_or_b32 v93, v93, 14, v94
	s_nop 1
	v_cndmask_b32_e64 v184, v184, 0, s[28:29]
	v_cndmask_b32_e64 v135, -1, v93, s[30:31]
	s_cmp_eq_u32 s25, 0
	s_cbranch_scc1 .Lfn_nodrop
	s_branch .Lfn_drop

.Lfn_w11:
	s_mov_b64 exec, s[22:23]
	s_mov_b64 exec, s[58:59]
	v_mov_b32_e32 v40, s11
	v_mov_b32_e32 v92, s19
	ds_write_b32 v40, v92
	s_mov_b64 exec, s[22:23]
	v_mov_b32_e32 v143, s24
	s_branch .LBB0_222
.Lfn_retry:
	s_cmp_eq_u32 s14, s25
	s_cbranch_scc1 .Lfn_orig
	s_mov_b32 s14, s25
	ds_write_b128 v127, a[206:209]
	s_branch .Lfn_rebin
.Lfn_orig:
	v_mov_b32_e32 v143, s24
	s_movk_i32 s4, 0x300
	v_mul_lo_u32 v9, v9, s4
	v_lshl_add_u32 v27, v9, 2, 0
	v_lshl_add_u32 v10, v190, 2, v27
	ds_read2st64_b32 v[10:11], v10 offset1:1
	s_add_i32 s4, 0, 0x18000
	v_lshl_add_u32 v33, v9, 1, s4
	v_cmp_lt_u32_e64 s[4:5], v0, v8
	v_lshl_add_u32 v9, v190, 1, v33
	s_waitcnt lgkmcnt(0)
	v_not_b32_e32 v12, v10
	v_cmp_gt_i32_e32 vcc, 0, v10
	v_lshl_add_u32 v14, v192, 1, v33
	v_lshl_add_u32 v16, v191, 2, v27
	v_cndmask_b32_e64 v40, -|v10|, v12, vcc
	v_lshl_add_u32 v10, v192, 2, v27
	v_lshl_add_u32 v17, v191, 1, v33
	v_cndmask_b32_e64 v18, 0, v0, s[4:5]
	v_lshl_add_u32 v19, v18, 2, v27
	v_lshl_add_u32 v18, v18, 1, v33
	ds_read_u16 v20, v9
	ds_read_u16 v9, v9 offset:128
	ds_read_b32 v10, v10
	ds_read_u16 v14, v14
	ds_read_b32 v16, v16
	ds_read_u16 v17, v17
	ds_read_b32 v22, v19
	ds_read_u16 v24, v18
	s_waitcnt lgkmcnt(7)
	v_sub_co_u32_sdwa v53, vcc, s66, v20 dst_sel:DWORD dst_unused:UNUSED_PAD src0_sel:DWORD src1_sel:WORD_0
	s_waitcnt lgkmcnt(6)
	v_and_b32_e32 v9, 0xffff, v9
	v_not_b32_e32 v18, v11
	v_cmp_gt_i32_e32 vcc, 0, v11
	v_lshlrev_b64 v[12:13], 14, v[40:41]
	v_mov_b32_e32 v56, 0x3fff
	v_cndmask_b32_e64 v40, -|v11|, v18, vcc
	v_sub_co_u32_e32 v49, vcc, s66, v9
	s_waitcnt lgkmcnt(4)
	v_and_b32_e32 v9, 0xffff, v14
	v_not_b32_e32 v11, v10
	v_cmp_gt_i32_e32 vcc, 0, v10
	v_lshlrev_b64 v[28:29], 14, v[40:41]
	v_cmp_lt_u32_e64 s[6:7], v1, v8
	v_cndmask_b32_e64 v40, -|v10|, v11, vcc
	v_sub_co_u32_e32 v45, vcc, s66, v9
	s_waitcnt lgkmcnt(2)
	v_and_b32_e32 v9, 0xffff, v17
	v_not_b32_e32 v10, v16
	v_cmp_gt_i32_e32 vcc, 0, v16
	v_lshlrev_b64 v[20:21], 14, v[40:41]
	v_cmp_lt_u32_e64 s[8:9], v2, v8
	v_cndmask_b32_e64 v40, -|v16|, v10, vcc
	v_sub_co_u32_e32 v37, vcc, s66, v9
	s_waitcnt lgkmcnt(1)
	v_cndmask_b32_e64 v9, 0, v22, s[4:5]
	v_not_b32_e32 v10, v9
	v_cmp_gt_i32_e32 vcc, 0, v9
	v_lshlrev_b64 v[18:19], 14, v[40:41]
	v_cmp_lt_u32_e64 s[10:11], v3, v8
	v_cndmask_b32_e64 v40, -|v9|, v10, vcc
	s_waitcnt lgkmcnt(0)
	v_sub_u32_e32 v9, 0x3fff, v24
	v_cndmask_b32_e64 v14, v56, v9, s[4:5]
	v_cndmask_b32_e64 v9, 0, v1, s[6:7]
	v_cndmask_b32_e64 v11, 0, v2, s[8:9]
	v_cndmask_b32_e64 v24, 0, v3, s[10:11]
	v_cmp_lt_u32_e64 s[12:13], v6, v8
	v_lshl_add_u32 v10, v9, 2, v27
	v_lshl_add_u32 v9, v9, 1, v33
	v_lshl_add_u32 v22, v11, 2, v27
	v_lshl_add_u32 v11, v11, 1, v33
	v_lshl_add_u32 v25, v24, 2, v27
	v_lshl_add_u32 v24, v24, 1, v33
	v_cndmask_b32_e64 v26, 0, v6, s[12:13]
	v_lshl_add_u32 v30, v26, 2, v27
	v_lshl_add_u32 v26, v26, 1, v33
	ds_read_b32 v10, v10
	ds_read_u16 v9, v9
	ds_read_b32 v22, v22
	ds_read_u16 v11, v11
	ds_read_b32 v25, v25
	ds_read_u16 v24, v24
	ds_read_b32 v32, v30
	ds_read_u16 v34, v26
	s_waitcnt lgkmcnt(7)
	v_cndmask_b32_e64 v10, 0, v10, s[6:7]
	s_waitcnt lgkmcnt(6)
	v_sub_u32_e32 v9, 0x3fff, v9
	v_not_b32_e32 v26, v10
	v_cmp_gt_i32_e32 vcc, 0, v10
	v_cndmask_b32_e64 v48, v56, v9, s[6:7]
	s_waitcnt lgkmcnt(5)
	v_cndmask_b32_e64 v9, 0, v22, s[8:9]
	v_lshlrev_b64 v[16:17], 14, v[40:41]
	v_cndmask_b32_e64 v40, -|v10|, v26, vcc
	v_not_b32_e32 v10, v9
	v_cmp_gt_i32_e32 vcc, 0, v9
	v_lshlrev_b64 v[50:51], 14, v[40:41]
	v_cmp_lt_u32_e64 s[14:15], v7, v8
	v_cndmask_b32_e64 v40, -|v9|, v10, vcc
	s_waitcnt lgkmcnt(4)
	v_sub_u32_e32 v9, 0x3fff, v11
	v_cndmask_b32_e64 v36, v56, v9, s[8:9]
	s_waitcnt lgkmcnt(3)
	v_cndmask_b32_e64 v9, 0, v25, s[10:11]
	v_not_b32_e32 v10, v9
	v_cmp_gt_i32_e32 vcc, 0, v9
	v_lshlrev_b64 v[38:39], 14, v[40:41]
	v_cmp_lt_u32_e64 s[16:17], v4, v8
	v_cndmask_b32_e64 v40, -|v9|, v10, vcc
	s_waitcnt lgkmcnt(2)
	v_sub_u32_e32 v9, 0x3fff, v24
	v_cndmask_b32_e64 v26, v56, v9, s[10:11]
	s_waitcnt lgkmcnt(1)
	v_cndmask_b32_e64 v9, 0, v32, s[12:13]
	v_not_b32_e32 v10, v9
	v_cmp_gt_i32_e32 vcc, 0, v9
	v_lshlrev_b64 v[30:31], 14, v[40:41]
	v_cmp_lt_u32_e64 s[18:19], v5, v8
	v_cndmask_b32_e64 v40, -|v9|, v10, vcc
	s_waitcnt lgkmcnt(0)
	v_sub_u32_e32 v9, 0x3fff, v34
	v_cndmask_b32_e64 v22, v56, v9, s[12:13]
	v_cndmask_b32_e64 v9, 0, v7, s[14:15]
	v_cndmask_b32_e64 v11, 0, v4, s[16:17]
	v_cndmask_b32_e64 v8, 0, v5, s[18:19]
	v_lshl_add_u32 v10, v9, 2, v27
	v_lshl_add_u32 v9, v9, 1, v33
	v_lshl_add_u32 v32, v11, 2, v27
	v_lshl_add_u32 v11, v11, 1, v33
	v_lshl_add_u32 v34, v8, 2, v27
	v_lshl_add_u32 v8, v8, 1, v33
	ds_read_b32 v10, v10
	ds_read_u16 v9, v9
	ds_read_b32 v32, v32
	ds_read_u16 v11, v11
	ds_read_b32 v34, v34
	ds_read_u16 v8, v8
	s_waitcnt lgkmcnt(5)
	v_cndmask_b32_e64 v10, 0, v10, s[14:15]
	s_waitcnt lgkmcnt(4)
	v_sub_u32_e32 v9, 0x3fff, v9
	v_not_b32_e32 v35, v10
	v_cmp_gt_i32_e32 vcc, 0, v10
	v_cndmask_b32_e64 v52, v56, v9, s[14:15]
	s_waitcnt lgkmcnt(3)
	v_cndmask_b32_e64 v9, 0, v32, s[16:17]
	v_lshlrev_b64 v[24:25], 14, v[40:41]
	v_cndmask_b32_e64 v40, -|v10|, v35, vcc
	v_not_b32_e32 v10, v9
	v_cmp_gt_i32_e32 vcc, 0, v9
	v_lshlrev_b64 v[54:55], 14, v[40:41]
	v_or_b32_e32 v12, v12, v53
	v_cndmask_b32_e64 v40, -|v9|, v10, vcc
	s_waitcnt lgkmcnt(2)
	v_sub_u32_e32 v9, 0x3fff, v11
	v_cndmask_b32_e64 v44, v56, v9, s[16:17]
	s_waitcnt lgkmcnt(1)
	v_cndmask_b32_e64 v9, 0, v34, s[18:19]
	v_or_b32_e32 v28, v28, v49
	v_not_b32_e32 v10, v9
	v_cmp_gt_i32_e32 vcc, 0, v9
	v_readfirstlane_b32 s21, v12
	v_or_b32_e32 v20, v20, v45
	v_or_b32_e32 v18, v18, v37
	v_lshlrev_b64 v[46:47], 14, v[40:41]
	v_cndmask_b32_e64 v40, -|v9|, v10, vcc
	s_waitcnt lgkmcnt(0)
	v_sub_u32_e32 v8, 0x3fff, v8
	v_xor_b32_e32 v9, s21, v12
	v_xor_b32_e32 v11, s21, v28
	v_or_b32_e32 v16, v16, v14
	v_or_b32_e32 v50, v50, v48
	v_cndmask_b32_e64 v32, v56, v8, s[18:19]
	v_or_b32_e32 v9, v11, v9
	v_xor_b32_e32 v11, s21, v20
	v_xor_b32_e32 v56, s21, v18
	v_or3_b32 v9, v9, v11, v56
	v_xor_b32_e32 v11, s21, v16
	v_xor_b32_e32 v56, s21, v50
	v_or_b32_e32 v38, v38, v36
	v_or_b32_e32 v30, v30, v26
	v_cndmask_b32_e64 v11, 0, v11, s[4:5]
	v_cndmask_b32_e64 v56, 0, v56, s[6:7]
	v_or3_b32 v9, v9, v11, v56
	v_xor_b32_e32 v11, s21, v38
	v_xor_b32_e32 v56, s21, v30
	v_or_b32_e32 v24, v24, v22
	v_or_b32_e32 v54, v54, v52
	v_readfirstlane_b32 s20, v13
	v_cndmask_b32_e64 v11, 0, v11, s[8:9]
	v_cndmask_b32_e64 v56, 0, v56, s[10:11]
	v_lshlrev_b64 v[34:35], 14, v[40:41]
	v_xor_b32_e32 v8, s20, v13
	v_xor_b32_e32 v10, s20, v29
	v_or3_b32 v9, v9, v11, v56
	v_xor_b32_e32 v11, s21, v24
	v_xor_b32_e32 v56, s21, v54
	v_or_b32_e32 v46, v46, v44
	v_or_b32_e32 v34, v34, v32
	v_or_b32_e32 v8, v10, v8
	v_xor_b32_e32 v10, s20, v21
	v_xor_b32_e32 v40, s20, v19
	v_cndmask_b32_e64 v11, 0, v11, s[12:13]
	v_cndmask_b32_e64 v56, 0, v56, s[14:15]
	v_or3_b32 v8, v8, v10, v40
	v_xor_b32_e32 v10, s20, v17
	v_xor_b32_e32 v40, s20, v51
	v_or3_b32 v9, v9, v11, v56
	v_xor_b32_e32 v11, s21, v46
	v_xor_b32_e32 v56, s21, v34
	v_cndmask_b32_e64 v10, 0, v10, s[4:5]
	v_cndmask_b32_e64 v40, 0, v40, s[6:7]
	v_cndmask_b32_e64 v11, 0, v11, s[16:17]
	v_cndmask_b32_e64 v56, 0, v56, s[18:19]
	v_or3_b32 v8, v8, v10, v40
	v_xor_b32_e32 v10, s20, v39
	v_xor_b32_e32 v40, s20, v31
	v_or3_b32 v9, v9, v11, v56
	v_cndmask_b32_e64 v10, 0, v10, s[8:9]
	v_cndmask_b32_e64 v40, 0, v40, s[10:11]
	v_or_b32_dpp v9, v9, v9 quad_perm:[1,0,3,2] row_mask:0xf bank_mask:0xf bound_ctrl:1
	v_or3_b32 v8, v8, v10, v40
	v_xor_b32_e32 v10, s20, v25
	v_xor_b32_e32 v40, s20, v55
	v_or_b32_dpp v9, v9, v9 quad_perm:[2,3,0,1] row_mask:0xf bank_mask:0xf bound_ctrl:1
	v_cndmask_b32_e64 v10, 0, v10, s[12:13]
	v_cndmask_b32_e64 v40, 0, v40, s[14:15]
	v_or_b32_dpp v9, v9, v9 row_half_mirror row_mask:0xf bank_mask:0xf bound_ctrl:1
	v_or3_b32 v8, v8, v10, v40
	v_xor_b32_e32 v10, s20, v47
	v_xor_b32_e32 v40, s20, v35
	v_or_b32_dpp v9, v9, v9 row_mirror row_mask:0xf bank_mask:0xf bound_ctrl:1
	v_cndmask_b32_e64 v10, 0, v10, s[16:17]
	v_cndmask_b32_e64 v40, 0, v40, s[18:19]
	v_readlane_b32 s20, v9, 0
	v_readlane_b32 s21, v9, 16
	v_or3_b32 v10, v8, v10, v40
	s_or_b32 s20, s21, s20
	v_readlane_b32 s21, v9, 32
	s_or_b32 s20, s20, s21
	v_readlane_b32 s21, v9, 48
	v_or_b32_dpp v9, v10, v10 quad_perm:[1,0,3,2] row_mask:0xf bank_mask:0xf bound_ctrl:1
	v_cndmask_b32_e64 v8, 0, 1, s[10:11]
	s_or_b32 s20, s20, s21
	v_or_b32_dpp v9, v9, v9 quad_perm:[2,3,0,1] row_mask:0xf bank_mask:0xf bound_ctrl:1
	v_lshlrev_b16_e32 v11, 8, v8
	v_cndmask_b32_e64 v8, 0, 1, s[6:7]
	v_or_b32_dpp v9, v9, v9 row_half_mirror row_mask:0xf bank_mask:0xf bound_ctrl:1
	v_lshlrev_b16_e32 v8, 8, v8
	v_mov_b32_e32 v40, 8
	v_or_b32_dpp v9, v9, v9 row_mirror row_mask:0xf bank_mask:0xf bound_ctrl:1
	v_lshrrev_b32_sdwa v40, v40, v8 dst_sel:BYTE_1 dst_unused:UNUSED_PAD src0_sel:DWORD src1_sel:DWORD
	v_readlane_b32 s21, v9, 0
	v_readlane_b32 s22, v9, 16
	s_or_b32 s21, s22, s21
	v_readlane_b32 s22, v9, 32
	s_or_b32 s21, s21, s22
	v_readlane_b32 s22, v9, 48
	v_cndmask_b32_e64 v8, 0, 1, s[14:15]
	s_or_b32 s21, s21, s22
	v_lshlrev_b16_e32 v8, 8, v8
	v_cndmask_b32_e64 v56, 0, 1, s[12:13]
	s_flbit_i32_b64 s22, s[20:21]
	v_or_b32_e32 v8, v56, v8
	v_cndmask_b32_e64 v56, 0, 1, s[18:19]
	s_sub_i32 s22, 56, s22
	v_cndmask_b32_e64 v10, 0, 1, s[4:5]
	v_lshlrev_b16_e32 v56, 8, v56
	v_cndmask_b32_e64 v57, 0, 1, s[16:17]
	s_max_i32 s22, s22, 0
	v_or_b32_e32 v10, v10, v40
	v_cndmask_b32_e64 v40, 0, 1, s[8:9]
	v_or_b32_sdwa v56, v57, v56 dst_sel:WORD_1 dst_unused:UNUSED_PAD src0_sel:DWORD src1_sel:DWORD
	s_cmp_lg_u64 s[20:21], 0
	v_or_b32_sdwa v11, v40, v11 dst_sel:WORD_1 dst_unused:UNUSED_PAD src0_sel:DWORD src1_sel:DWORD
	v_or_b32_sdwa v8, v8, v56 dst_sel:DWORD dst_unused:UNUSED_PAD src0_sel:WORD_0 src1_sel:DWORD
	s_cselect_b32 s56, s22, 0
	v_mov_b32_e32 v9, 0x1010101
	v_or_b32_sdwa v10, v10, v11 dst_sel:DWORD dst_unused:UNUSED_PAD src0_sel:WORD_0 src1_sel:DWORD
	s_movk_i32 s55, 0x100
	v_mov_b32_e32 v40, 8
	s_branch .LBB0_226
